# baseline (speedup 1.0000x reference)
; DI void attn_prompt_unit(const Args& a, int b, int c, int g, LAS unsigned char* lds, const int tid) {
;     ...
;     for (int kt = 0; kt < 6; ++kt) if ((kt >> 1) >= s0) {
; #pragma unroll
;         for (int i = 0; i < 16; ++i) { const float pv = exp2f((sc[kt][i] - mx) * LOG2E); sc[kt][i] = pv; sum += pv; } }
;     sum += __shfl_xor(sum, 32);
;     const float inv = 1.0f / (sum + exp2f((sink - mx) * LOG2E));
;     f32x16 o[2];
; #pragma unroll
;     for (int i = 0; i < 16; ++i) { o[0][i] = 0.f; o[1][i] = 0.f; }
; #pragma unroll
;     for (int kt = 0; kt < 6; ++kt) if ((kt >> 1) >= s0) {
.LBB0_378:
	v_sub_f32_e32 v80, v80, v97
	v_mul_f32_e32 v99, 0x3fb8aa3b, v80
	v_sub_f32_e32 v81, v81, v97
	v_sub_f32_e32 v64, v64, v97
	v_sub_u32_e32 v108, v108, v160
	s_movk_i32 s2, 0x190
	v_exp_f32_e32 v99, v99
	s_nop 0
	v_add_f32_e32 v80, v99, v100
	v_mul_f32_e32 v100, 0x3fb8aa3b, v81
	v_exp_f32_e32 v100, v100
	v_sub_f32_e32 v81, v82, v97
	v_mul_f32_e32 v82, 0x3fb8aa3b, v81
	v_add_f32_e32 v80, v100, v80
	s_nop 0
	v_exp_f32_e32 v101, v82
	v_sub_f32_e32 v81, v83, v97
	v_mul_f32_e32 v82, 0x3fb8aa3b, v81
	v_add_f32_e32 v80, v101, v80
	s_nop 0
	v_exp_f32_e32 v102, v82
	v_sub_f32_e32 v81, v84, v97
	v_mul_f32_e32 v82, 0x3fb8aa3b, v81
	v_add_f32_e32 v80, v102, v80
	s_nop 0
	v_exp_f32_e32 v103, v82
	v_sub_f32_e32 v81, v85, v97
	v_mul_f32_e32 v82, 0x3fb8aa3b, v81
	v_add_f32_e32 v80, v103, v80
	s_nop 0
	v_exp_f32_e32 v104, v82
	v_sub_f32_e32 v81, v86, v97
	v_mul_f32_e32 v82, 0x3fb8aa3b, v81
	v_add_f32_e32 v80, v104, v80
	s_nop 0
	v_exp_f32_e32 v105, v82
	v_sub_f32_e32 v81, v87, v97
	v_mul_f32_e32 v82, 0x3fb8aa3b, v81
	v_add_f32_e32 v80, v105, v80
	s_nop 0
	v_exp_f32_e32 v107, v82
	v_sub_f32_e32 v81, v88, v97
	v_mul_f32_e32 v82, 0x3fb8aa3b, v81
	v_add_f32_e32 v80, v107, v80
	s_nop 0
	v_exp_f32_e32 v106, v82
	v_sub_f32_e32 v81, v89, v97
	v_mul_f32_e32 v82, 0x3fb8aa3b, v81
	v_add_f32_e32 v80, v106, v80
	s_nop 0
	v_exp_f32_e32 v109, v82
	v_sub_f32_e32 v81, v90, v97
	v_mul_f32_e32 v82, 0x3fb8aa3b, v81
	v_add_f32_e32 v80, v109, v80
	s_nop 0
	v_exp_f32_e32 v110, v82
	v_sub_f32_e32 v81, v91, v97
	v_mul_f32_e32 v82, 0x3fb8aa3b, v81
	v_add_f32_e32 v80, v110, v80
	s_nop 0
	v_exp_f32_e32 v111, v82
	v_sub_f32_e32 v81, v92, v97
	v_mul_f32_e32 v82, 0x3fb8aa3b, v81
	v_add_f32_e32 v80, v111, v80
	s_nop 0
	v_exp_f32_e32 v114, v82
	v_sub_f32_e32 v81, v93, v97
	v_mul_f32_e32 v82, 0x3fb8aa3b, v81
	v_add_f32_e32 v80, v114, v80
	s_nop 0
	v_exp_f32_e32 v115, v82
	v_sub_f32_e32 v81, v94, v97
	v_mul_f32_e32 v82, 0x3fb8aa3b, v81
	v_add_f32_e32 v80, v115, v80
	s_nop 0
	v_exp_f32_e32 v116, v82
	v_sub_f32_e32 v81, v95, v97
	v_mul_f32_e32 v82, 0x3fb8aa3b, v81
	v_add_f32_e32 v80, v116, v80
	s_nop 0
	v_exp_f32_e32 v121, v82
	v_mul_f32_e32 v81, 0x3fb8aa3b, v64
	v_add_f32_e32 v80, v121, v80
	s_nop 0
	v_exp_f32_e32 v120, v81
	v_sub_f32_e32 v64, v65, v97
	v_mul_f32_e32 v65, 0x3fb8aa3b, v64
	v_exp_f32_e32 v122, v65
	v_sub_f32_e32 v64, v66, v97
	v_mul_f32_e32 v65, 0x3fb8aa3b, v64
	v_exp_f32_e32 v123, v65
	v_sub_f32_e32 v64, v67, v97
	v_mul_f32_e32 v65, 0x3fb8aa3b, v64
	v_exp_f32_e32 v124, v65
	v_sub_f32_e32 v64, v68, v97
	v_mul_f32_e32 v65, 0x3fb8aa3b, v64
	v_exp_f32_e32 v125, v65
	v_sub_f32_e32 v64, v69, v97
	v_mul_f32_e32 v65, 0x3fb8aa3b, v64
	v_exp_f32_e32 v126, v65
	v_sub_f32_e32 v64, v70, v97
	v_mul_f32_e32 v65, 0x3fb8aa3b, v64
	v_exp_f32_e32 v127, v65
	v_sub_f32_e32 v64, v71, v97
	v_mul_f32_e32 v65, 0x3fb8aa3b, v64
	v_exp_f32_e32 v129, v65
	v_sub_f32_e32 v64, v72, v97
	v_mul_f32_e32 v65, 0x3fb8aa3b, v64
	v_exp_f32_e32 v128, v65
	v_sub_f32_e32 v64, v73, v97
	v_mul_f32_e32 v65, 0x3fb8aa3b, v64
	v_exp_f32_e32 v130, v65
	v_sub_f32_e32 v64, v74, v97
	v_mul_f32_e32 v65, 0x3fb8aa3b, v64
	v_exp_f32_e32 v131, v65
	v_sub_f32_e32 v64, v75, v97
	v_mul_f32_e32 v65, 0x3fb8aa3b, v64
	v_exp_f32_e32 v133, v65
	v_sub_f32_e32 v64, v76, v97
	v_mul_f32_e32 v65, 0x3fb8aa3b, v64
	v_exp_f32_e32 v134, v65
	v_sub_f32_e32 v64, v77, v97
	v_mul_f32_e32 v65, 0x3fb8aa3b, v64
	v_exp_f32_e32 v135, v65
	v_sub_f32_e32 v64, v78, v97
	v_mul_f32_e32 v65, 0x3fb8aa3b, v64
	v_exp_f32_e32 v136, v65
	v_sub_f32_e32 v64, v79, v97
	v_mul_f32_e32 v65, 0x3fb8aa3b, v64
	s_nop 1
	s_and_b64 vcc, exec, s[42:43]
	v_exp_f32_e32 v138, v65
	v_add_f32_e32 v64, v120, v80
	v_add_f32_e32 v64, v122, v64
	v_add_f32_e32 v64, v123, v64
	v_add_f32_e32 v64, v124, v64
	v_add_f32_e32 v64, v125, v64
	v_add_f32_e32 v64, v126, v64
	v_add_f32_e32 v64, v127, v64
	v_add_f32_e32 v64, v129, v64
	v_add_f32_e32 v64, v128, v64
	v_add_f32_e32 v64, v130, v64
	v_add_f32_e32 v64, v131, v64
	v_add_f32_e32 v64, v133, v64
	v_add_f32_e32 v64, v134, v64
	v_add_f32_e32 v64, v135, v64
	v_add_f32_e32 v64, v136, v64
	v_add_f32_e32 v137, v138, v64
	ds_bpermute_b32 v98, v98, v137
	v_mad_u32_u24 v64, v118, s2, v108
	v_add_u32_e32 v139, 0x9800, v64
	v_add_u32_e32 v140, 0x6800, v64
	s_cbranch_vccz .LBB0_388
	v_mov_b32_e32 v78, v161
	v_mov_b32_e32 v79, v161
	v_mov_b32_e32 v64, v161
	v_mov_b32_e32 v65, v161
	v_mov_b32_e32 v66, v161
	v_mov_b32_e32 v67, v161
	v_mov_b32_e32 v68, v161
	v_mov_b32_e32 v69, v161
	v_mov_b32_e32 v70, v161
	v_mov_b32_e32 v71, v161
	v_mov_b32_e32 v72, v161
	v_mov_b32_e32 v73, v161
	v_mov_b32_e32 v74, v161
	v_mov_b32_e32 v75, v161
	v_mov_b32_e32 v76, v161
	v_mov_b32_e32 v77, v161
	v_mov_b64_e32 v[94:95], v[78:79]
	v_mov_b64_e32 v[92:93], v[76:77]
	v_mov_b64_e32 v[90:91], v[74:75]
	v_mov_b64_e32 v[88:89], v[72:73]
	v_mov_b64_e32 v[86:87], v[70:71]
	v_mov_b64_e32 v[84:85], v[68:69]
	v_mov_b64_e32 v[82:83], v[66:67]
	v_mov_b64_e32 v[80:81], v[64:65]
	s_and_b64 vcc, exec, s[42:43]
	s_cbranch_vccnz .LBB0_381

; #define LAS __attribute__((address_space(3)))
; DI unsigned pk2(float lo, float hi) { const f32x2_t v = {lo, hi}; const bf16x2_t b = __builtin_convertvector(v, bf16x2_t); return __builtin_bit_cast(unsigned, b); }
; DI void attn_prompt_unit(const Args& a, int b, int c, int g, LAS unsigned char* lds, const int tid) {
;     ...
;     const float inv = 1.0f / (sum + exp2f((sink - mx) * LOG2E));
;     f32x16 o[2];
; #pragma unroll
;     for (int i = 0; i < 16; ++i) { o[0][i] = 0.f; o[1][i] = 0.f; }
; #pragma unroll
;     for (int kt = 0; kt < 6; ++kt) if ((kt >> 1) >= s0) {
;         s16x4 vlo[2][2], vhi[2][2];
; #pragma unroll
;         for (int s = 0; s < 2; ++s)
; #pragma unroll
;             for (int dt = 0; dt < 2; ++dt) { const LAS bf16_t* vp = Vt + (dt * 32 + r) * 200 + 32 * kt + 16 * s + 4 * h; vlo[s][dt] = *(const LAS s16x4*)vp; vhi[s][dt] = *(const LAS s16x4*)(vp + 8); }
;         __builtin_amdgcn_sched_barrier(0);
; #pragma unroll
;         for (int s = 0; s < 2; ++s) {
;             u32x4 pw;
; #pragma unroll
;             for (int e = 0; e < 4; ++e) pw[e] = pk2(sc[kt][8 * s + 2 * e], sc[kt][8 * s + 2 * e + 1]);
;             const bf16x8 pf = __builtin_bit_cast(bf16x8, pw);
; #pragma unroll
;             for (int dt = 0; dt < 2; ++dt)
;                 o[dt] = __builtin_amdgcn_mfma_f32_32x32x16_bf16(__builtin_shufflevector(vlo[s][dt], vhi[s][dt], 0, 1, 2, 3, 4, 5, 6, 7), pf, o[dt], 0, 0, 0);
;         }
;         __builtin_amdgcn_sched_barrier(0);
;     }
;     bf16_t* orow = MIX + qrow * LDMIX + (g * 4 + j) * 64;
; #pragma unroll
;     for (int dt = 0; dt < 2; ++dt)
; #pragma unroll
;         for (int i4 = 0; i4 < 4; ++i4) { u32x2 w; w.x = pk2(o[dt][4 * i4] * inv, o[dt][4 * i4 + 1] * inv); w.y = pk2(o[dt][4 * i4 + 2] * inv, o[dt][4 * i4 + 3] * inv);
;             *(u32x2*)(orow + dt * 32 + 8 * i4 + 4 * h) = w; }
.LBB0_387:
	v_add_u32_e32 v0, v108, v50
	v_add_u32_e32 v8, v108, v51
	v_add_u32_e32 v52, 0x6800, v0
	v_add_u32_e32 v53, 0x6800, v8
	ds_read2_b64 v[0:3], v52 offset0:160 offset1:162
	ds_read2_b64 v[4:7], v52 offset0:164 offset1:166
	ds_read2_b64 v[8:11], v53 offset0:160 offset1:162
	ds_read2_b64 v[12:15], v53 offset0:164 offset1:166
	v_cvt_pk_bf16_f32 v48, v99, v100
	v_cvt_pk_bf16_f32 v49, v101, v102
	v_cvt_pk_bf16_f32 v50, v103, v104
	v_cvt_pk_bf16_f32 v51, v105, v107
	s_waitcnt lgkmcnt(3)
	s_nop 0
	v_mfma_f32_32x32x16_bf16 v[32:47], v[0:3], v[48:51], v[32:47]
	v_cvt_pk_bf16_f32 v0, v106, v109
	v_cvt_pk_bf16_f32 v1, v110, v111
	v_cvt_pk_bf16_f32 v2, v114, v115
	v_cvt_pk_bf16_f32 v3, v116, v121
	s_waitcnt lgkmcnt(1)
	v_mfma_f32_32x32x16_bf16 v[16:31], v[8:11], v[48:51], v[16:31]
	v_mfma_f32_32x32x16_bf16 v[32:47], v[4:7], v[0:3], v[32:47]
	s_waitcnt lgkmcnt(0)
	v_mfma_f32_32x32x16_bf16 v[16:31], v[12:15], v[0:3], v[16:31]
	ds_read2_b64 v[0:3], v52 offset0:168 offset1:170
	ds_read2_b64 v[4:7], v52 offset0:172 offset1:174
	ds_read2_b64 v[8:11], v53 offset0:168 offset1:170
	ds_read2_b64 v[12:15], v53 offset0:172 offset1:174
	v_cvt_pk_bf16_f32 v48, v120, v122
	v_cvt_pk_bf16_f32 v49, v123, v124
	v_cvt_pk_bf16_f32 v50, v125, v126
	v_cvt_pk_bf16_f32 v51, v127, v129
	s_waitcnt lgkmcnt(3)
	s_nop 0
	v_mfma_f32_32x32x16_bf16 v[32:47], v[0:3], v[48:51], v[32:47]
	v_cvt_pk_bf16_f32 v0, v128, v130
	v_cvt_pk_bf16_f32 v1, v131, v133
	v_cvt_pk_bf16_f32 v2, v134, v135
	v_cvt_pk_bf16_f32 v3, v136, v138
	s_waitcnt lgkmcnt(1)
	v_mfma_f32_32x32x16_bf16 v[16:31], v[8:11], v[48:51], v[16:31]
	v_mfma_f32_32x32x16_bf16 v[32:47], v[4:7], v[0:3], v[32:47]
	s_waitcnt lgkmcnt(0)
	v_mfma_f32_32x32x16_bf16 v[16:31], v[12:15], v[0:3], v[16:31]
	v_sub_f32_e32 v0, v96, v97
	v_mul_f32_e32 v1, 0x3fb8aa3b, v0
	v_exp_f32_e32 v0, v1
	v_add_f32_e32 v1, v137, v98
	v_add_f32_e32 v0, v0, v1
	v_div_scale_f32 v1, s[0:1], v0, v0, 1.0
	v_rcp_f32_e32 v2, v1
	v_div_scale_f32 v3, vcc, 1.0, v0, 1.0
	v_readlane_b32 s0, v254, 13
	v_fma_f32 v4, -v1, v2, 1.0
	v_fmac_f32_e32 v2, v4, v2
	v_mul_f32_e32 v4, v3, v2
	v_fma_f32 v5, -v1, v4, v3
	v_fmac_f32_e32 v4, v5, v2
	v_fma_f32 v1, -v1, v4, v3
	v_readlane_b32 s1, v254, 14
	v_div_fmas_f32 v1, v1, v2, v4
	v_div_fixup_f32 v0, v1, v0, 1.0
	v_mov_b64_e32 v[2:3], s[0:1]
	v_mad_u64_u32 v[2:3], s[0:1], v117, s27, v[2:3]
	v_mad_u32_u24 v3, v119, s27, v3
	v_lshl_add_u64 v[2:3], v[112:113], 1, v[2:3]
	v_pk_mul_f32 v[4:5], v[0:1], v[32:33] op_sel_hi:[0,1]
	v_pk_mul_f32 v[6:7], v[0:1], v[34:35] op_sel_hi:[0,1]
	v_lshl_add_u64 v[2:3], v[2:3], 0, v[160:161]
	v_cvt_pk_bf16_f32 v4, v4, v5
	v_cvt_pk_bf16_f32 v5, v6, v7
	global_store_dwordx2 v[2:3], v[4:5], off
	v_pk_mul_f32 v[4:5], v[0:1], v[36:37] op_sel_hi:[0,1]
	v_pk_mul_f32 v[6:7], v[0:1], v[38:39] op_sel_hi:[0,1]
	v_cvt_pk_bf16_f32 v4, v4, v5
	v_cvt_pk_bf16_f32 v5, v6, v7
	global_store_dwordx2 v[2:3], v[4:5], off offset:16
	v_pk_mul_f32 v[4:5], v[0:1], v[40:41] op_sel_hi:[0,1]
	v_pk_mul_f32 v[6:7], v[0:1], v[42:43] op_sel_hi:[0,1]
	v_cvt_pk_bf16_f32 v4, v4, v5
	v_cvt_pk_bf16_f32 v5, v6, v7
	global_store_dwordx2 v[2:3], v[4:5], off offset:32
	v_pk_mul_f32 v[4:5], v[0:1], v[44:45] op_sel_hi:[0,1]
	v_pk_mul_f32 v[6:7], v[0:1], v[46:47] op_sel_hi:[0,1]
	v_cvt_pk_bf16_f32 v4, v4, v5
	v_cvt_pk_bf16_f32 v5, v6, v7
	global_store_dwordx2 v[2:3], v[4:5], off offset:48
	v_pk_mul_f32 v[4:5], v[0:1], v[16:17] op_sel_hi:[0,1]
	v_pk_mul_f32 v[6:7], v[0:1], v[18:19] op_sel_hi:[0,1]
	v_cvt_pk_bf16_f32 v4, v4, v5
	v_cvt_pk_bf16_f32 v5, v6, v7
	global_store_dwordx2 v[2:3], v[4:5], off offset:64
	v_pk_mul_f32 v[4:5], v[0:1], v[20:21] op_sel_hi:[0,1]
	v_pk_mul_f32 v[6:7], v[0:1], v[22:23] op_sel_hi:[0,1]
	v_cvt_pk_bf16_f32 v4, v4, v5
	v_cvt_pk_bf16_f32 v5, v6, v7
	global_store_dwordx2 v[2:3], v[4:5], off offset:80
	v_pk_mul_f32 v[4:5], v[0:1], v[24:25] op_sel_hi:[0,1]
	v_pk_mul_f32 v[6:7], v[0:1], v[26:27] op_sel_hi:[0,1]
	v_cvt_pk_bf16_f32 v4, v4, v5
	v_cvt_pk_bf16_f32 v5, v6, v7
	global_store_dwordx2 v[2:3], v[4:5], off offset:96
	v_pk_mul_f32 v[4:5], v[0:1], v[28:29] op_sel_hi:[0,1]
	v_pk_mul_f32 v[0:1], v[0:1], v[30:31] op_sel_hi:[0,1]
	v_cvt_pk_bf16_f32 v4, v4, v5
	v_cvt_pk_bf16_f32 v5, v0, v1
	global_store_dwordx2 v[2:3], v[4:5], off offset:112
	s_barrier
	s_cbranch_execz .LBB0_165
	s_branch .LBB0_242
